# all three context-row GEMMs (merge/out/down ctx units): K-chunk granular 4-stage LDS ring with three chunks in flight, fragment reads batched before the MFMAs, gate bytes preloaded
# baseline (speedup 1.0000x reference)
.LBB1_639:
	s_lshl_b32 s6, s5, 12
	s_lshl_b32 s7, s1, 6
	s_and_b32 s72, s6, 0x1c0000
	s_and_b32 s7, s7, 0x1c0
	s_ashr_i32 s9, s1, 3
	v_lshl_add_u64 v[38:39], v[16:17], 0, s[72:73]
	v_lshl_add_u64 v[40:41], v[18:19], 0, s[72:73]
	s_bfe_u32 s6, s1, 0x20003
	s_or_b32 s72, s7, 0x2000
	s_and_b32 s7, s9, 0x3fffffc
	s_or_b32 s7, s7, s6
	s_lshl_b32 s18, s7, 6
	v_lshl_add_u64 v[0:1], s[72:73], 0, v[12:13]
	v_readlane_b32 s10, v254, 48
	s_ashr_i32 s19, s18, 31
	v_lshlrev_b64 v[0:1], 12, v[0:1]
	v_readlane_b32 s11, v254, 49
	v_mov_b32_e32 v25, v113
	v_lshl_add_u64 v[6:7], s[18:19], 0, v[12:13]
	v_lshl_add_u64 v[0:1], s[10:11], 0, v[0:1]
	s_mov_b32 m0, s2
	v_lshl_add_u64 v[2:3], v[0:1], 0, v[112:113]
	v_lshl_add_u64 v[0:1], v[0:1], 0, v[24:25]
	s_mov_b64 s[10:11], 0x4000
	v_lshlrev_b64 v[6:7], 12, v[6:7]
	s_waitcnt vmcnt(0) lgkmcnt(0)
	s_barrier
	v_lshl_add_u64 v[4:5], v[0:1], 0, s[10:11]
	v_lshl_add_u64 v[6:7], s[38:39], 0, v[6:7]
	global_load_lds_dwordx4 v[2:3], off
	s_add_i32 m0, s2, 0x400
	v_lshl_add_u64 v[8:9], v[6:7], 0, v[112:113]
	v_lshl_add_u64 v[6:7], v[6:7], 0, v[24:25]
	global_load_lds_dwordx4 v[4:5], off
	s_add_i32 m0, s2, 0x4000
	v_lshl_add_u64 v[10:11], v[6:7], 0, s[10:11]
	global_load_lds_dwordx4 v[8:9], off
	s_add_i32 m0, s2, 0x4400
	s_mov_b64 s[10:11], 0x100
	global_load_lds_dwordx4 v[10:11], off
	v_lshl_add_u64 v[2:3], v[2:3], 0, s[10:11]
	s_add_i32 m0, s2, 0x8000
	s_mov_b64 s[26:27], 0x4100
	global_load_lds_dwordx4 v[2:3], off
	v_lshl_add_u64 v[0:1], v[0:1], 0, s[26:27]
	s_add_i32 m0, s2, 0x8400
	v_add_u32_e32 v26, s72, v48
	global_load_lds_dwordx4 v[0:1], off
	v_lshl_add_u64 v[0:1], v[8:9], 0, s[10:11]
	s_add_i32 m0, s2, 0xc000
	s_lshl_b32 s10, s6, 6
	global_load_lds_dwordx4 v[0:1], off
	v_lshl_add_u64 v[0:1], v[6:7], 0, s[26:27]
	s_add_i32 m0, s2, 0xc400
	v_mad_i64_i32 v[36:37], s[6:7], v26, s46, 0
	global_load_lds_dwordx4 v[0:1], off
	v_mov_b64_e32 v[0:1], s[14:15]
	v_mad_i64_i32 v[0:1], s[6:7], v26, s46, v[0:1]
	s_lshl_b32 s6, s9, 6
	s_and_b32 s6, s6, 0xffffff00
	v_lshl_add_u64 v[0:1], v[0:1], 0, s[18:19]
	s_or_b32 s6, s6, s10
	v_lshl_add_u64 v[0:1], v[0:1], 0, v[14:15]
	s_ashr_i32 s7, s6, 31
	v_lshl_add_u64 v[42:43], v[0:1], 0, s[16:17]
	v_lshl_add_u64 v[0:1], v[12:13], 0, s[6:7]
	s_waitcnt vmcnt(0)
	s_barrier
	v_lshlrev_b64 v[0:1], 12, v[0:1]
	v_lshl_add_u64 v[44:45], v[20:21], 0, v[0:1]
	v_lshl_add_u64 v[46:47], v[22:23], 0, v[0:1]
	v_mov_b32_e32 v0, 0
	v_ashrrev_i32_e32 v27, 31, v26
	s_mov_b32 s6, 0
	v_mov_b32_e32 v28, v113
	v_mov_b32_e32 v29, v113
	v_mov_b32_e32 v30, v113
	v_mov_b32_e32 v31, v113
	v_mov_b32_e32 v32, v113
	v_mov_b32_e32 v33, v113
	v_mov_b32_e32 v34, v113
	v_mov_b32_e32 v35, v113
	s_mov_b64 s[26:27], 0
	s_mov_b32 s7, 0
	v_mov_b32_e32 v1, v0
	v_mov_b32_e32 v2, v0
	v_mov_b32_e32 v3, v0
	v_mov_b32_e32 v4, v0
	v_mov_b32_e32 v5, v0
	v_mov_b32_e32 v6, v0
	v_mov_b32_e32 v7, v0
	global_load_dword v114, v[42:43], off
	global_load_dword v115, v[42:43], off offset:16
	global_load_dword v116, v[42:43], off offset:2048
	global_load_dword v117, v[42:43], off offset:2064
	s_mov_b64 s[10:11], 0x1cb00000
	v_lshl_add_u64 v[60:61], v[38:39], 0, s[10:11]
	s_mov_b64 s[10:11], 0x1cb04000
	v_lshl_add_u64 v[62:63], v[40:41], 0, s[10:11]
	s_mov_b64 s[10:11], 0x2bd00000
	v_lshl_add_u64 v[64:65], v[44:45], 0, s[10:11]
	s_mov_b64 s[10:11], 0x2bd04000
	v_lshl_add_u64 v[66:67], v[46:47], 0, s[10:11]
	s_mov_b64 s[26:27], 0x200
	s_add_i32 s9, s2, 0x10000
	v_lshl_add_u64 v[104:105], v[60:61], 0, s[26:27]
	s_mov_b32 m0, s9
	s_nop 0
	global_load_lds_dwordx4 v[104:105], off
	v_lshl_add_u64 v[104:105], v[62:63], 0, s[26:27]
	s_add_i32 m0, s9, 0x400
	s_nop 0
	global_load_lds_dwordx4 v[104:105], off
	v_lshl_add_u64 v[104:105], v[64:65], 0, s[26:27]
	s_add_i32 m0, s9, 0x4000
	s_nop 0
	global_load_lds_dwordx4 v[104:105], off
	v_lshl_add_u64 v[104:105], v[66:67], 0, s[26:27]
	s_add_i32 m0, s9, 0x4400
	s_nop 0
	global_load_lds_dwordx4 v[104:105], off
	s_mov_b64 s[26:27], 0x300
	s_mov_b32 s7, 0
.Lcg0_loop:
	s_cmp_gt_u32 s7, 12
	s_cbranch_scc1 .Lcg0_nodma
	s_add_i32 s9, s7, 3
	s_and_b32 s9, s9, 3
	s_lshl_b32 s9, s9, 15
	s_add_i32 s9, s9, s2
	v_lshl_add_u64 v[104:105], v[60:61], 0, s[26:27]
	s_mov_b32 m0, s9
	s_nop 0
	global_load_lds_dwordx4 v[104:105], off
	v_lshl_add_u64 v[104:105], v[62:63], 0, s[26:27]
	s_add_i32 m0, s9, 0x400
	s_nop 0
	global_load_lds_dwordx4 v[104:105], off
	v_lshl_add_u64 v[104:105], v[64:65], 0, s[26:27]
	s_add_i32 m0, s9, 0x4000
	s_nop 0
	global_load_lds_dwordx4 v[104:105], off
	v_lshl_add_u64 v[104:105], v[66:67], 0, s[26:27]
	s_add_i32 m0, s9, 0x4400
	s_nop 0
	global_load_lds_dwordx4 v[104:105], off
	s_add_u32 s26, s26, 0x100
	s_addc_u32 s27, s27, 0
.Lcg0_nodma:
	s_and_b32 s9, s7, 3
	s_lshl_b32 s9, s9, 15
	v_add_u32_e32 v106, s9, v49
	s_add_i32 s11, s9, s3
	v_add_u32_e32 v107, s11, v50
	v_add_u32_e32 v108, v106, v51
	v_add_u32_e32 v109, v107, v51
	ds_read_b128 v[118:121], v108
	ds_read_b128 v[122:125], v109 offset:16384
	ds_read_b128 v[126:129], v109 offset:20480
	v_add_u32_e32 v108, v106, v52
	v_add_u32_e32 v109, v107, v52
	ds_read_b128 v[68:71], v108
	ds_read_b128 v[72:75], v109 offset:16384
	ds_read_b128 v[76:79], v109 offset:20480
	v_add_u32_e32 v108, v106, v53
	v_add_u32_e32 v109, v107, v53
	ds_read_b128 v[80:83], v108
	ds_read_b128 v[84:87], v109 offset:16384
	ds_read_b128 v[88:91], v109 offset:20480
	v_add_u32_e32 v108, v106, v54
	v_add_u32_e32 v109, v107, v54
	ds_read_b128 v[92:95], v108
	ds_read_b128 v[96:99], v109 offset:16384
	ds_read_b128 v[100:103], v109 offset:20480
	s_waitcnt lgkmcnt(9)
	v_mfma_f32_16x16x32_bf16 v[0:3], v[122:125], v[118:121], v[0:3]
	v_mfma_f32_16x16x32_bf16 v[4:7], v[126:129], v[118:121], v[4:7]
	s_waitcnt lgkmcnt(6)
	v_mfma_f32_16x16x32_bf16 v[0:3], v[72:75], v[68:71], v[0:3]
	v_mfma_f32_16x16x32_bf16 v[4:7], v[76:79], v[68:71], v[4:7]
	s_waitcnt lgkmcnt(3)
	v_mfma_f32_16x16x32_bf16 v[0:3], v[84:87], v[80:83], v[0:3]
	v_mfma_f32_16x16x32_bf16 v[4:7], v[88:91], v[80:83], v[4:7]
	s_waitcnt lgkmcnt(0)
	v_mfma_f32_16x16x32_bf16 v[0:3], v[96:99], v[92:95], v[0:3]
	v_mfma_f32_16x16x32_bf16 v[4:7], v[100:103], v[92:95], v[4:7]
	s_cmp_eq_u32 s7, 3
	s_cbranch_scc0 .Lcg0_nh3
	v_cvt_f32_ubyte0_e32 v104, v114
	v_cvt_f32_ubyte1_e32 v105, v114
	v_cvt_f32_ubyte2_e32 v106, v114
	v_cvt_f32_ubyte3_e32 v107, v114
	v_cvt_f32_ubyte0_e32 v108, v115
	v_cvt_f32_ubyte1_e32 v109, v115
	v_cvt_f32_ubyte2_e32 v110, v115
	v_cvt_f32_ubyte3_e32 v111, v115
	v_pk_mul_f32 v[104:105], v[104:105], s[28:29] op_sel_hi:[1,0]
	v_pk_mul_f32 v[106:107], v[106:107], s[28:29] op_sel_hi:[1,0]
	v_pk_mul_f32 v[108:109], v[108:109], s[28:29] op_sel_hi:[1,0]
	v_pk_mul_f32 v[110:111], v[110:111], s[28:29] op_sel_hi:[1,0]
	v_pk_fma_f32 v[28:29], v[0:1], v[104:105], v[28:29]
	v_pk_fma_f32 v[30:31], v[2:3], v[106:107], v[30:31]
	v_pk_fma_f32 v[32:33], v[4:5], v[108:109], v[32:33]
	v_pk_fma_f32 v[34:35], v[6:7], v[110:111], v[34:35]
	v_mov_b32_e32 v0, 0
	v_mov_b32_e32 v1, 0
	v_mov_b32_e32 v2, 0
	v_mov_b32_e32 v3, 0
	v_mov_b32_e32 v4, 0
	v_mov_b32_e32 v5, 0
	v_mov_b32_e32 v6, 0
	v_mov_b32_e32 v7, 0
.Lcg0_nh3:
	s_cmp_eq_u32 s7, 7
	s_cbranch_scc0 .Lcg0_nh7
	v_cvt_f32_ubyte0_e32 v104, v116
	v_cvt_f32_ubyte1_e32 v105, v116
	v_cvt_f32_ubyte2_e32 v106, v116
	v_cvt_f32_ubyte3_e32 v107, v116
	v_cvt_f32_ubyte0_e32 v108, v117
	v_cvt_f32_ubyte1_e32 v109, v117
	v_cvt_f32_ubyte2_e32 v110, v117
	v_cvt_f32_ubyte3_e32 v111, v117
	v_pk_mul_f32 v[104:105], v[104:105], s[28:29] op_sel_hi:[1,0]
	v_pk_mul_f32 v[106:107], v[106:107], s[28:29] op_sel_hi:[1,0]
	v_pk_mul_f32 v[108:109], v[108:109], s[28:29] op_sel_hi:[1,0]
	v_pk_mul_f32 v[110:111], v[110:111], s[28:29] op_sel_hi:[1,0]
	v_pk_fma_f32 v[28:29], v[0:1], v[104:105], v[28:29]
	v_pk_fma_f32 v[30:31], v[2:3], v[106:107], v[30:31]
	v_pk_fma_f32 v[32:33], v[4:5], v[108:109], v[32:33]
	v_pk_fma_f32 v[34:35], v[6:7], v[110:111], v[34:35]
	v_mov_b32_e32 v0, 0
	v_mov_b32_e32 v1, 0
	v_mov_b32_e32 v2, 0
	v_mov_b32_e32 v3, 0
	v_mov_b32_e32 v4, 0
	v_mov_b32_e32 v5, 0
	v_mov_b32_e32 v6, 0
	v_mov_b32_e32 v7, 0
.Lcg0_nh7:
	s_cmp_gt_u32 s7, 12
	s_cbranch_scc1 .Lcg0_tail
	s_waitcnt vmcnt(8)
	s_branch .Lcg0_bar

.Lcg0_bar:
	s_barrier
	s_add_i32 s7, s7, 1
	s_cmp_lt_u32 s7, 14
	s_cbranch_scc1 .Lcg0_loop
	s_nop 7
	v_mov_b32_e32 v59, v1
	v_mov_b32_e32 v60, v2
	v_mov_b32_e32 v25, v3
	v_mov_b32_e32 v8, v4
	v_mov_b32_e32 v9, v5
	v_mov_b32_e32 v10, v6
	v_mov_b32_e32 v11, v7
	s_branch .LBB1_638

.LBB1_804:
	s_lshl_b32 s9, s7, 12
	s_lshl_b32 s10, s1, 6
	s_and_b32 s72, s9, 0x1c0000
	s_and_b32 s10, s10, 0x1c0
	v_lshl_add_u64 v[8:9], v[18:19], 0, s[72:73]
	v_lshl_add_u64 v[10:11], v[20:21], 0, s[72:73]
	s_or_b32 s72, s10, 0x2000
	s_ashr_i32 s10, s1, 3
	s_bfe_u32 s9, s1, 0x20003
	s_and_b32 s11, s10, 0x3fffffc
	s_or_b32 s11, s11, s9
	s_lshl_b32 s30, s11, 6
	v_lshl_add_u64 v[0:1], s[72:73], 0, v[16:17]
	v_readlane_b32 s24, v254, 62
	s_ashr_i32 s31, s30, 31
	v_lshlrev_b64 v[0:1], 12, v[0:1]
	v_readlane_b32 s25, v254, 63
	v_mov_b32_e32 v27, v113
	v_lshl_add_u64 v[6:7], s[30:31], 0, v[16:17]
	v_lshl_add_u64 v[0:1], s[24:25], 0, v[0:1]
	s_mov_b32 m0, s5
	v_lshl_add_u64 v[2:3], v[0:1], 0, v[112:113]
	v_lshl_add_u64 v[0:1], v[0:1], 0, v[26:27]
	s_mov_b64 s[24:25], 0x4000
	v_lshlrev_b64 v[6:7], 12, v[6:7]
	s_waitcnt vmcnt(0) lgkmcnt(0)
	s_barrier
	v_lshl_add_u64 v[4:5], v[0:1], 0, s[24:25]
	v_lshl_add_u64 v[6:7], s[16:17], 0, v[6:7]
	global_load_lds_dwordx4 v[2:3], off
	s_add_i32 m0, s5, 0x400
	v_lshl_add_u64 v[12:13], v[6:7], 0, v[112:113]
	v_lshl_add_u64 v[6:7], v[6:7], 0, v[26:27]
	global_load_lds_dwordx4 v[4:5], off
	s_add_i32 m0, s5, 0x4000
	v_lshl_add_u64 v[14:15], v[6:7], 0, s[24:25]
	global_load_lds_dwordx4 v[12:13], off
	s_add_i32 m0, s5, 0x4400
	s_mov_b64 s[24:25], 0x100
	global_load_lds_dwordx4 v[14:15], off
	v_lshl_add_u64 v[2:3], v[2:3], 0, s[24:25]
	s_add_i32 m0, s5, 0x8000
	s_mov_b64 s[36:37], 0x4100
	global_load_lds_dwordx4 v[2:3], off
	v_lshl_add_u64 v[0:1], v[0:1], 0, s[36:37]
	s_add_i32 m0, s5, 0x8400
	s_lshl_b32 s10, s10, 6
	global_load_lds_dwordx4 v[0:1], off
	v_lshl_add_u64 v[0:1], v[12:13], 0, s[24:25]
	s_add_i32 m0, s5, 0xc000
	s_lshl_b32 s9, s9, 6
	global_load_lds_dwordx4 v[0:1], off
	v_lshl_add_u64 v[0:1], v[6:7], 0, s[36:37]
	s_add_i32 m0, s5, 0xc400
	s_and_b32 s10, s10, 0xffffff00
	global_load_lds_dwordx4 v[0:1], off
	s_or_b32 s10, s10, s9
	s_ashr_i32 s11, s10, 31
	v_lshl_add_u64 v[0:1], v[16:17], 0, s[10:11]
	s_waitcnt vmcnt(0)
	s_barrier
	v_lshlrev_b64 v[0:1], 12, v[0:1]
	v_lshl_add_u64 v[12:13], v[22:23], 0, v[0:1]
	v_lshl_add_u64 v[14:15], v[24:25], 0, v[0:1]
	v_mov_b32_e32 v0, 0
	v_mov_b32_e32 v1, v0
	v_mov_b32_e32 v2, v0
	v_mov_b32_e32 v3, v0
	v_mov_b32_e32 v4, v0
	v_mov_b32_e32 v5, v0
	v_mov_b32_e32 v6, v0
	v_mov_b32_e32 v7, v0
	s_mov_b64 s[24:25], 0x23100000
	v_lshl_add_u64 v[60:61], v[8:9], 0, s[24:25]
	s_mov_b64 s[24:25], 0x23104000
	v_lshl_add_u64 v[62:63], v[10:11], 0, s[24:25]
	s_mov_b64 s[24:25], 0x2c500000
	v_lshl_add_u64 v[64:65], v[12:13], 0, s[24:25]
	s_mov_b64 s[24:25], 0x2c504000
	v_lshl_add_u64 v[66:67], v[14:15], 0, s[24:25]
	s_mov_b64 s[36:37], 0x200
	s_add_i32 s9, s5, 0x10000
	v_lshl_add_u64 v[104:105], v[60:61], 0, s[36:37]
	s_mov_b32 m0, s9
	s_nop 0
	global_load_lds_dwordx4 v[104:105], off
	v_lshl_add_u64 v[104:105], v[62:63], 0, s[36:37]
	s_add_i32 m0, s9, 0x400
	s_nop 0
	global_load_lds_dwordx4 v[104:105], off
	v_lshl_add_u64 v[104:105], v[64:65], 0, s[36:37]
	s_add_i32 m0, s9, 0x4000
	s_nop 0
	global_load_lds_dwordx4 v[104:105], off
	v_lshl_add_u64 v[104:105], v[66:67], 0, s[36:37]
	s_add_i32 m0, s9, 0x4400
	s_nop 0
	global_load_lds_dwordx4 v[104:105], off
	s_mov_b64 s[36:37], 0x300
	s_mov_b32 s10, 0
.Lcg1_loop:
	s_cmp_gt_u32 s10, 12
	s_cbranch_scc1 .Lcg1_nodma
	s_add_i32 s9, s10, 3
	s_and_b32 s9, s9, 3
	s_lshl_b32 s9, s9, 15
	s_add_i32 s9, s9, s5
	v_lshl_add_u64 v[104:105], v[60:61], 0, s[36:37]
	s_mov_b32 m0, s9
	s_nop 0
	global_load_lds_dwordx4 v[104:105], off
	v_lshl_add_u64 v[104:105], v[62:63], 0, s[36:37]
	s_add_i32 m0, s9, 0x400
	s_nop 0
	global_load_lds_dwordx4 v[104:105], off
	v_lshl_add_u64 v[104:105], v[64:65], 0, s[36:37]
	s_add_i32 m0, s9, 0x4000
	s_nop 0
	global_load_lds_dwordx4 v[104:105], off
	v_lshl_add_u64 v[104:105], v[66:67], 0, s[36:37]
	s_add_i32 m0, s9, 0x4400
	s_nop 0
	global_load_lds_dwordx4 v[104:105], off
	s_add_u32 s36, s36, 0x100
	s_addc_u32 s37, s37, 0
.Lcg1_nodma:
	s_and_b32 s9, s10, 3
	s_lshl_b32 s9, s9, 15
	v_add_u32_e32 v106, s9, v35
	s_add_i32 s11, s9, s6
	v_add_u32_e32 v107, s11, v36
	v_add_u32_e32 v108, v106, v37
	v_add_u32_e32 v109, v107, v37
	ds_read_b128 v[46:49], v108
	ds_read_b128 v[50:53], v109 offset:16384
	ds_read_b128 v[54:57], v109 offset:20480
	v_add_u32_e32 v108, v106, v38
	v_add_u32_e32 v109, v107, v38
	ds_read_b128 v[68:71], v108
	ds_read_b128 v[72:75], v109 offset:16384
	ds_read_b128 v[76:79], v109 offset:20480
	v_add_u32_e32 v108, v106, v39
	v_add_u32_e32 v109, v107, v39
	ds_read_b128 v[80:83], v108
	ds_read_b128 v[84:87], v109 offset:16384
	ds_read_b128 v[88:91], v109 offset:20480
	v_add_u32_e32 v108, v106, v40
	v_add_u32_e32 v109, v107, v40
	ds_read_b128 v[92:95], v108
	ds_read_b128 v[96:99], v109 offset:16384
	ds_read_b128 v[100:103], v109 offset:20480
	s_waitcnt lgkmcnt(9)
	v_mfma_f32_16x16x32_bf16 v[0:3], v[50:53], v[46:49], v[0:3]
	v_mfma_f32_16x16x32_bf16 v[4:7], v[54:57], v[46:49], v[4:7]
	s_waitcnt lgkmcnt(6)
	v_mfma_f32_16x16x32_bf16 v[0:3], v[72:75], v[68:71], v[0:3]
	v_mfma_f32_16x16x32_bf16 v[4:7], v[76:79], v[68:71], v[4:7]
	s_waitcnt lgkmcnt(3)
	v_mfma_f32_16x16x32_bf16 v[0:3], v[84:87], v[80:83], v[0:3]
	v_mfma_f32_16x16x32_bf16 v[4:7], v[88:91], v[80:83], v[4:7]
	s_waitcnt lgkmcnt(0)
	v_mfma_f32_16x16x32_bf16 v[0:3], v[96:99], v[92:95], v[0:3]
	v_mfma_f32_16x16x32_bf16 v[4:7], v[100:103], v[92:95], v[4:7]
	s_cmp_gt_u32 s10, 12
	s_cbranch_scc1 .Lcg1_tail
	s_waitcnt vmcnt(8)
	s_branch .Lcg1_bar

.Lcg1_bar:
	s_barrier
	s_add_i32 s10, s10, 1
	s_cmp_lt_u32 s10, 14
	s_cbranch_scc1 .Lcg1_loop
	v_add_u32_e32 v12, v43, v37
	ds_read_b128 v[8:11], v12 offset:16384
	v_add_u32_e32 v27, v44, v37
	ds_read_b128 v[12:15], v12 offset:20480
	ds_read_b128 v[28:31], v27
	v_add_u32_e32 v27, v43, v38
	v_add_u32_e32 v32, v44, v38
	s_waitcnt lgkmcnt(0)
	v_mfma_f32_16x16x32_bf16 v[4:7], v[12:15], v[28:31], v[4:7]
	ds_read_b128 v[46:49], v32
	ds_read_b128 v[12:15], v27 offset:20480
	s_and_b64 vcc, exec, s[18:19]
	v_mfma_f32_16x16x32_bf16 v[0:3], v[8:11], v[28:31], v[0:3]
	ds_read_b128 v[8:11], v27 offset:16384
	v_add_u32_e32 v27, v43, v39
	ds_read_b128 v[28:31], v27 offset:16384
	v_add_u32_e32 v32, v44, v39
	s_waitcnt lgkmcnt(0)
	v_mfma_f32_16x16x32_bf16 v[0:3], v[8:11], v[46:49], v[0:3]
	ds_read_b128 v[8:11], v27 offset:20480
	ds_read_b128 v[50:53], v32
	v_add_u32_e32 v27, v43, v40
	v_add_u32_e32 v32, v42, v37
	v_mfma_f32_16x16x32_bf16 v[4:7], v[12:15], v[46:49], v[4:7]
	v_add_u32_e32 v12, v44, v40
	ds_read_b128 v[12:15], v12
	s_waitcnt lgkmcnt(0)
	v_mfma_f32_16x16x32_bf16 v[0:3], v[28:31], v[50:53], v[0:3]
	ds_read_b128 v[28:31], v27 offset:16384
	v_mfma_f32_16x16x32_bf16 v[4:7], v[8:11], v[50:53], v[4:7]
	ds_read_b128 v[8:11], v27 offset:20480
	v_add_u32_e32 v27, v41, v37
	ds_read_b128 v[46:49], v27 offset:16384
	s_waitcnt lgkmcnt(0)
	v_mfma_f32_16x16x32_bf16 v[0:3], v[28:31], v[12:15], v[0:3]
	ds_read_b128 v[28:31], v27 offset:20480
	ds_read_b128 v[50:53], v32
	v_add_u32_e32 v27, v41, v38
	v_add_u32_e32 v32, v42, v39
	v_mfma_f32_16x16x32_bf16 v[4:7], v[8:11], v[12:15], v[4:7]
	v_add_u32_e32 v8, v42, v38
	ds_read_b128 v[8:11], v8
	ds_read_b128 v[12:15], v27 offset:16384
	s_waitcnt lgkmcnt(0)
	v_mfma_f32_16x16x32_bf16 v[4:7], v[28:31], v[50:53], v[4:7]
	ds_read_b128 v[28:31], v27 offset:20480
	v_add_u32_e32 v27, v41, v39
	v_mfma_f32_16x16x32_bf16 v[0:3], v[46:49], v[50:53], v[0:3]
	ds_read_b128 v[46:49], v27 offset:16384
	v_mfma_f32_16x16x32_bf16 v[0:3], v[12:15], v[8:11], v[0:3]
	ds_read_b128 v[12:15], v27 offset:20480
	ds_read_b128 v[50:53], v32
	v_add_u32_e32 v27, v41, v40
	v_add_u32_e32 v32, s72, v34
	s_waitcnt lgkmcnt(0)
	v_mfma_f32_16x16x32_bf16 v[4:7], v[28:31], v[8:11], v[4:7]
	v_add_u32_e32 v8, v42, v40
	ds_read_b128 v[54:57], v8
	v_or_b32_e32 v30, s30, v45
	v_mfma_f32_16x16x32_bf16 v[0:3], v[46:49], v[50:53], v[0:3]
	ds_read_b128 v[8:11], v27 offset:16384
	ds_read_b128 v[46:49], v27 offset:20480
	v_ashrrev_i32_e32 v31, 31, v30
	s_waitcnt vmcnt(0) lgkmcnt(0)
	s_barrier
	v_lshl_add_u64 v[28:29], v[30:31], 2, s[26:27]
	v_mfma_f32_16x16x32_bf16 v[12:15], v[12:15], v[50:53], v[4:7]
	v_ashrrev_i32_e32 v33, 31, v32
	s_mov_b64 s[30:31], -1
	s_waitcnt lgkmcnt(0)
	v_mfma_f32_16x16x32_bf16 v[4:7], v[8:11], v[54:57], v[0:3]
	global_load_dwordx4 v[8:11], v[28:29], off
	v_mfma_f32_16x16x32_bf16 v[0:3], v[46:49], v[54:57], v[12:15]
	s_nop 2
	v_lshlrev_b64 v[12:13], 12, v[32:33]
	v_lshl_add_u64 v[12:13], s[12:13], 0, v[12:13]
	v_lshl_add_u64 v[28:29], v[30:31], 1, v[12:13]
	s_cbranch_vccz .LBB1_808
	global_load_dwordx2 v[14:15], v[28:29], off
	s_mov_b64 s[30:31], 0
	s_waitcnt vmcnt(0)
	v_lshlrev_b32_e32 v12, 16, v14
	v_and_b32_e32 v13, 0xffff0000, v14
	v_lshlrev_b32_e32 v14, 16, v15
	v_and_b32_e32 v15, 0xffff0000, v15
